# final_norm: hoist the 8 serialized final_g loads to the top of each iteration and drop the per-chunk vmcnt(0) store ladder (epilogue de-serialisation); on top of shw_gemm DPP reduction
# baseline (speedup 1.0000x reference)
.LBB0_1307:
	v_ashrrev_i32_e32 v79, 31, v78
	v_lshlrev_b64 v[2:3], 13, v[78:79]
	v_lshl_add_u64 v[86:87], v[66:67], 0, v[2:3]
	v_add_co_u32_e32 v88, vcc, 0x2000, v86
	global_load_dwordx4 v[58:61], v[86:87], off
	global_load_dwordx4 v[54:57], v[86:87], off offset:1024
	global_load_dwordx4 v[46:49], v[86:87], off offset:2048
	global_load_dwordx4 v[34:37], v[86:87], off offset:3072
	v_addc_co_u32_e32 v89, vcc, 0, v87, vcc
	v_add_co_u32_e32 v82, vcc, 0x1000, v86
	global_load_dwordx4 v[62:65], v[88:89], off
	global_load_dwordx4 v[50:53], v[88:89], off offset:1024
	global_load_dwordx4 v[42:45], v[88:89], off offset:2048
	v_addc_co_u32_e32 v83, vcc, 0, v87, vcc
	global_load_dwordx4 v[30:33], v[82:83], off
	v_add_co_u32_e32 v84, vcc, 0x3000, v86
	v_add_u32_e32 v1, s7, v1
	s_nop 0
	v_addc_co_u32_e32 v85, vcc, 0, v87, vcc
	global_load_dwordx4 v[26:29], v[84:85], off
	global_load_dwordx4 v[38:41], v[88:89], off offset:3072
	global_load_dwordx4 v[22:25], v[82:83], off offset:1024
	global_load_dwordx4 v[18:21], v[84:85], off offset:1024
	global_load_dwordx4 v[14:17], v[82:83], off offset:2048
	global_load_dwordx4 v[2:5], v[82:83], off offset:3072
	global_load_dwordx4 v[10:13], v[84:85], off offset:2048
	global_load_dwordx4 v[6:9], v[84:85], off offset:3072
	global_load_dwordx4 v[120:123], v[68:69], off
	global_load_dwordx4 v[124:127], v[68:69], off offset:1024
	global_load_dwordx4 v[128:131], v[68:69], off offset:2048
	global_load_dwordx4 v[132:135], v[68:69], off offset:3072
	global_load_dwordx4 v[136:139], v[70:71], off
	global_load_dwordx4 v[140:143], v[72:73], off
	global_load_dwordx4 v[144:147], v[74:75], off
	global_load_dwordx4 v[148:151], v[76:77], off
	v_add_u32_e32 v78, s8, v78
	s_waitcnt vmcnt(23)
	v_mov_b32_e32 v98, v59
	s_waitcnt vmcnt(22)
	v_mov_b32_e32 v99, v55
	v_mov_b32_e32 v102, v61
	v_mov_b32_e32 v103, v57
	v_mov_b32_e32 v96, v58
	v_mov_b32_e32 v97, v54
	v_mov_b32_e32 v100, v60
	v_mov_b32_e32 v101, v56
	s_waitcnt vmcnt(21)
	v_pk_mul_f32 v[104:105], v[48:49], v[48:49]
	v_pk_mul_f32 v[106:107], v[46:47], v[46:47]
	v_pk_mul_f32 v[98:99], v[98:99], v[98:99]
	v_pk_mul_f32 v[102:103], v[102:103], v[102:103]
	v_pk_mov_b32 v[112:113], v[106:107], v[104:105] op_sel:[1,0]
	v_mov_b32_e32 v107, v105
	v_pk_fma_f32 v[96:97], v[96:97], v[96:97], v[98:99]
	v_pk_fma_f32 v[98:99], v[100:101], v[100:101], v[102:103]
	s_waitcnt vmcnt(20)
	v_mul_f32_e32 v108, v35, v35
	v_mul_f32_e32 v110, v37, v37
	s_waitcnt vmcnt(19)
	v_mov_b32_e32 v102, v63
	s_waitcnt vmcnt(18)
	v_mov_b32_e32 v103, v51
	v_mov_b32_e32 v114, v65
	v_mov_b32_e32 v115, v53
	v_pk_add_f32 v[106:107], v[112:113], v[106:107]
	v_pk_add_f32 v[96:97], v[96:97], v[98:99]
	v_pk_fma_f32 v[104:105], v[34:35], v[34:35], v[108:109] op_sel_hi:[1,1,0]
	v_pk_fma_f32 v[108:109], v[36:37], v[36:37], v[110:111] op_sel_hi:[1,1,0]
	v_mov_b32_e32 v100, v62
	v_mov_b32_e32 v101, v50
	v_mov_b32_e32 v110, v64
	v_mov_b32_e32 v111, v52
	s_waitcnt vmcnt(17)
	v_pk_mul_f32 v[112:113], v[44:45], v[44:45]
	v_pk_mul_f32 v[116:117], v[42:43], v[42:43]
	v_pk_mul_f32 v[98:99], v[102:103], v[102:103]
	v_pk_mul_f32 v[102:103], v[114:115], v[114:115]
	s_waitcnt vmcnt(16)
	v_mul_f32_e32 v79, v30, v30
	v_mul_f32_e32 v95, v31, v31
	v_pk_add_f32 v[106:107], v[106:107], v[106:107] op_sel:[0,1] op_sel_hi:[1,0]
	v_pk_add_f32 v[96:97], v[96:97], v[96:97] op_sel:[0,1] op_sel_hi:[1,0]
	v_pk_mov_b32 v[114:115], v[116:117], v[112:113] op_sel:[1,0]
	v_mov_b32_e32 v117, v113
	v_mul_f32_e32 v105, v32, v32
	v_mul_f32_e32 v109, v33, v33
	v_pk_fma_f32 v[98:99], v[100:101], v[100:101], v[98:99]
	v_pk_fma_f32 v[100:101], v[110:111], v[110:111], v[102:103]
	v_mov_b32_e32 v107, v95
	v_mov_b32_e32 v97, v79
	v_pk_add_f32 v[102:103], v[114:115], v[116:117]
	v_pk_add_f32 v[98:99], v[98:99], v[100:101]
	v_pk_add_f32 v[100:101], v[104:105], v[108:109]
	v_pk_add_f32 v[96:97], v[96:97], v[106:107]
	s_waitcnt vmcnt(15)
	v_mul_f32_e32 v95, v26, v26
	v_mul_f32_e32 v110, v27, v27
	v_pk_add_f32 v[96:97], v[96:97], v[100:101]
	v_pk_add_f32 v[98:99], v[98:99], v[98:99] op_sel:[0,1] op_sel_hi:[1,0]
	v_pk_add_f32 v[100:101], v[102:103], v[102:103] op_sel:[0,1] op_sel_hi:[1,0]
	v_mov_b32_e32 v99, v95
	v_mov_b32_e32 v101, v110
	v_pk_add_f32 v[98:99], v[98:99], v[100:101]
	s_waitcnt vmcnt(14)
	v_mul_f32_e32 v100, v39, v39
	v_mul_f32_e32 v102, v41, v41
	v_mul_f32_e32 v111, v28, v28
	v_mul_f32_e32 v112, v29, v29
	v_pk_fma_f32 v[100:101], v[38:39], v[38:39], v[100:101] op_sel_hi:[1,1,0]
	v_pk_fma_f32 v[102:103], v[40:41], v[40:41], v[102:103] op_sel_hi:[1,1,0]
	v_mov_b32_e32 v101, v111
	v_mov_b32_e32 v103, v112
	v_pk_add_f32 v[100:101], v[100:101], v[102:103]
	s_waitcnt vmcnt(13)
	v_pk_mul_f32 v[102:103], v[22:23], v[22:23]
	v_pk_add_f32 v[100:101], v[98:99], v[100:101]
	v_pk_mul_f32 v[98:99], v[24:25], v[24:25]
	s_waitcnt vmcnt(10)
	v_mul_f32_e32 v79, v2, v2
	v_pk_mov_b32 v[104:105], v[102:103], v[98:99] op_sel:[1,0]
	v_mov_b32_e32 v103, v99
	v_pk_add_f32 v[98:99], v[104:105], v[102:103]
	v_mul_f32_e32 v95, v3, v3
	v_pk_add_f32 v[96:97], v[96:97], v[96:97] op_sel:[0,1] op_sel_hi:[1,0]
	v_pk_add_f32 v[98:99], v[98:99], v[98:99] op_sel:[0,1] op_sel_hi:[1,0]
	v_pk_mul_f32 v[102:103], v[20:21], v[20:21]
	v_pk_mul_f32 v[104:105], v[18:19], v[18:19]
	v_mov_b32_e32 v97, v79
	v_mov_b32_e32 v99, v95
	v_pk_mov_b32 v[106:107], v[104:105], v[102:103] op_sel:[1,0]
	v_mov_b32_e32 v105, v103
	v_pk_add_f32 v[96:97], v[96:97], v[98:99]
	v_mul_f32_e32 v98, v15, v15
	v_pk_add_f32 v[102:103], v[106:107], v[104:105]
	v_mul_f32_e32 v104, v4, v4
	v_pk_fma_f32 v[98:99], v[14:15], v[14:15], v[98:99] op_sel_hi:[1,1,0]
	v_mul_f32_e32 v106, v5, v5
	v_mov_b32_e32 v99, v104
	v_mul_f32_e32 v104, v17, v17
	v_pk_fma_f32 v[104:105], v[16:17], v[16:17], v[104:105] op_sel_hi:[1,1,0]
	s_waitcnt vmcnt(8)
	v_mul_f32_e32 v79, v6, v6
	v_mov_b32_e32 v105, v106
	v_pk_add_f32 v[98:99], v[98:99], v[104:105]
	v_mul_f32_e32 v95, v7, v7
	v_pk_add_f32 v[104:105], v[96:97], v[98:99]
	s_nop 0
	v_pk_add_f32 v[100:101], v[100:101], v[100:101] op_sel:[0,1] op_sel_hi:[1,0]
	v_pk_add_f32 v[102:103], v[102:103], v[102:103] op_sel:[0,1] op_sel_hi:[1,0]
	v_mov_b32_e32 v101, v79
	v_mov_b32_e32 v103, v95
	v_pk_add_f32 v[100:101], v[100:101], v[102:103]
	v_mul_f32_e32 v102, v11, v11
	v_mul_f32_e32 v106, v8, v8
	v_pk_fma_f32 v[102:103], v[10:11], v[10:11], v[102:103] op_sel_hi:[1,1,0]
	v_mul_f32_e32 v108, v9, v9
	v_mov_b32_e32 v103, v106
	v_mul_f32_e32 v106, v13, v13
	v_pk_fma_f32 v[106:107], v[12:13], v[12:13], v[106:107] op_sel_hi:[1,1,0]
	s_nop 0
	v_mov_b32_e32 v107, v108
	v_pk_add_f32 v[102:103], v[102:103], v[106:107]
	s_nop 0
	v_pk_add_f32 v[100:101], v[100:101], v[102:103]
	v_mov_b32_e32 v103, v104
	v_mov_b32_e32 v102, v100
	v_mov_b32_e32 v104, v101
	v_pk_add_f32 v[100:101], v[102:103], v[104:105]
	ds_bpermute_b32 v103, v81, v101
	ds_bpermute_b32 v102, v81, v100
	s_waitcnt lgkmcnt(0)
	v_pk_add_f32 v[100:101], v[100:101], v[102:103]
	ds_bpermute_b32 v103, v90, v101
	ds_bpermute_b32 v102, v90, v100
	s_waitcnt lgkmcnt(0)
	v_pk_add_f32 v[100:101], v[100:101], v[102:103]
	ds_bpermute_b32 v103, v91, v101
	ds_bpermute_b32 v102, v91, v100
	s_waitcnt lgkmcnt(0)
	v_pk_add_f32 v[100:101], v[100:101], v[102:103]
	ds_bpermute_b32 v103, v92, v101
	ds_bpermute_b32 v102, v92, v100
	s_waitcnt lgkmcnt(0)
	v_pk_add_f32 v[100:101], v[100:101], v[102:103]
	ds_bpermute_b32 v103, v93, v101
	ds_bpermute_b32 v102, v93, v100
	s_waitcnt lgkmcnt(0)
	v_pk_add_f32 v[100:101], v[100:101], v[102:103]
	ds_bpermute_b32 v103, v94, v101
	ds_bpermute_b32 v102, v94, v100
	s_waitcnt lgkmcnt(0)
	v_pk_add_f32 v[100:101], v[100:101], v[102:103]
	s_nop 0
	v_pk_fma_f32 v[100:101], v[100:101], s[6:7], v[80:81] op_sel_hi:[1,0,0]
	s_nop 0
	v_mul_f32_e32 v79, 0x4b800000, v101
	v_cmp_gt_f32_e32 vcc, s9, v101
	v_mul_f32_e32 v95, 0x4b800000, v100
	v_cmp_gt_f32_e64 s[0:1], s9, v100
	v_cndmask_b32_e32 v79, v101, v79, vcc
	v_rsq_f32_e32 v79, v79
	v_cndmask_b32_e64 v95, v100, v95, s[0:1]
	v_rsq_f32_e32 v95, v95
	v_mul_f32_e32 v100, 0x45800000, v79
	v_cndmask_b32_e32 v100, v79, v100, vcc
	v_mul_f32_e32 v79, 0x45800000, v95
	v_pk_mul_f32 v[58:59], v[58:59], v[100:101] op_sel_hi:[1,0]
	v_pk_mul_f32 v[60:61], v[60:61], v[100:101] op_sel_hi:[1,0]
	v_cndmask_b32_e64 v102, v95, v79, s[0:1]
	s_waitcnt vmcnt(0)
	v_pk_mul_f32 v[60:61], v[122:123], v[60:61]
	v_pk_mul_f32 v[58:59], v[120:121], v[58:59]
	global_store_dwordx4 v[86:87], v[58:61], off
	v_pk_mul_f32 v[56:57], v[56:57], v[100:101] op_sel_hi:[1,0]
	v_pk_mul_f32 v[54:55], v[54:55], v[100:101] op_sel_hi:[1,0]
	v_pk_mul_f32 v[58:59], v[62:63], v[102:103] op_sel_hi:[1,0]
	v_pk_mul_f32 v[60:61], v[64:65], v[102:103] op_sel_hi:[1,0]
	v_pk_mul_f32 v[58:59], v[120:121], v[58:59]
	v_pk_mul_f32 v[60:61], v[122:123], v[60:61]
	global_store_dwordx4 v[88:89], v[58:61], off
	s_nop 0
	v_pk_mul_f32 v[62:63], v[52:53], v[102:103] op_sel_hi:[1,0]
	v_pk_mul_f32 v[64:65], v[50:51], v[102:103] op_sel_hi:[1,0]
	v_pk_mul_f32 v[48:49], v[48:49], v[100:101] op_sel_hi:[1,0]
	v_pk_mul_f32 v[46:47], v[46:47], v[100:101] op_sel_hi:[1,0]
	v_pk_mul_f32 v[36:37], v[36:37], v[100:101] op_sel_hi:[1,0]
	v_pk_mul_f32 v[34:35], v[34:35], v[100:101] op_sel_hi:[1,0]
	v_pk_mul_f32 v[40:41], v[40:41], v[102:103] op_sel_hi:[1,0]
	v_pk_mul_f32 v[38:39], v[38:39], v[102:103] op_sel_hi:[1,0]
	v_pk_mul_f32 v[32:33], v[32:33], v[100:101] op_sel_hi:[1,0]
	v_pk_mul_f32 v[30:31], v[30:31], v[100:101] op_sel_hi:[1,0]
	v_pk_mul_f32 v[24:25], v[24:25], v[100:101] op_sel_hi:[1,0]
	v_pk_mul_f32 v[22:23], v[22:23], v[100:101] op_sel_hi:[1,0]
	v_pk_mul_f32 v[16:17], v[16:17], v[100:101] op_sel_hi:[1,0]
	v_pk_mul_f32 v[14:15], v[14:15], v[100:101] op_sel_hi:[1,0]
	v_cmp_lt_i32_e32 vcc, s10, v1
	v_pk_mul_f32 v[4:5], v[4:5], v[100:101] op_sel_hi:[1,0]
	v_pk_mul_f32 v[2:3], v[2:3], v[100:101] op_sel_hi:[1,0]
	s_or_b64 s[2:3], vcc, s[2:3]
	v_pk_mul_f32 v[8:9], v[8:9], v[102:103] op_sel_hi:[1,0]
	v_pk_mul_f32 v[6:7], v[6:7], v[102:103] op_sel_hi:[1,0]
	s_nop 0
	v_pk_mul_f32 v[50:51], v[124:125], v[54:55]
	v_pk_mul_f32 v[52:53], v[126:127], v[56:57]
	v_pk_mul_f32 v[54:55], v[124:125], v[64:65]
	v_pk_mul_f32 v[56:57], v[126:127], v[62:63]
	global_store_dwordx4 v[86:87], v[50:53], off offset:1024
	global_store_dwordx4 v[88:89], v[54:57], off offset:1024
	s_nop 0
	s_nop 0
	v_pk_mul_f32 v[54:55], v[44:45], v[102:103] op_sel_hi:[1,0]
	v_pk_mul_f32 v[56:57], v[42:43], v[102:103] op_sel_hi:[1,0]
	s_nop 0
	v_pk_mul_f32 v[42:43], v[128:129], v[46:47]
	v_pk_mul_f32 v[44:45], v[130:131], v[48:49]
	v_pk_mul_f32 v[46:47], v[128:129], v[56:57]
	v_pk_mul_f32 v[48:49], v[130:131], v[54:55]
	global_store_dwordx4 v[86:87], v[42:45], off offset:2048
	global_store_dwordx4 v[88:89], v[46:49], off offset:2048
	s_nop 0
	s_nop 0
	v_pk_mul_f32 v[34:35], v[132:133], v[34:35]
	v_pk_mul_f32 v[36:37], v[134:135], v[36:37]
	v_pk_mul_f32 v[38:39], v[132:133], v[38:39]
	v_pk_mul_f32 v[40:41], v[134:135], v[40:41]
	global_store_dwordx4 v[86:87], v[34:37], off offset:3072
	global_store_dwordx4 v[88:89], v[38:41], off offset:3072
	s_nop 0
	s_nop 0
	v_pk_mul_f32 v[38:39], v[28:29], v[102:103] op_sel_hi:[1,0]
	v_pk_mul_f32 v[40:41], v[26:27], v[102:103] op_sel_hi:[1,0]
	s_nop 0
	v_pk_mul_f32 v[26:27], v[30:31], v[136:137]
	v_pk_mul_f32 v[28:29], v[32:33], v[138:139]
	v_pk_mul_f32 v[30:31], v[40:41], v[136:137]
	v_pk_mul_f32 v[32:33], v[38:39], v[138:139]
	global_store_dwordx4 v[82:83], v[26:29], off
	global_store_dwordx4 v[84:85], v[30:33], off
	s_nop 0
	s_nop 0
	v_pk_mul_f32 v[30:31], v[20:21], v[102:103] op_sel_hi:[1,0]
	v_pk_mul_f32 v[32:33], v[18:19], v[102:103] op_sel_hi:[1,0]
	s_nop 0
	v_pk_mul_f32 v[18:19], v[22:23], v[140:141]
	v_pk_mul_f32 v[20:21], v[24:25], v[142:143]
	v_pk_mul_f32 v[22:23], v[32:33], v[140:141]
	v_pk_mul_f32 v[24:25], v[30:31], v[142:143]
	global_store_dwordx4 v[82:83], v[18:21], off offset:1024
	global_store_dwordx4 v[84:85], v[22:25], off offset:1024
	s_nop 0
	s_nop 0
	v_pk_mul_f32 v[22:23], v[12:13], v[102:103] op_sel_hi:[1,0]
	v_pk_mul_f32 v[24:25], v[10:11], v[102:103] op_sel_hi:[1,0]
	s_nop 0
	v_pk_mul_f32 v[10:11], v[14:15], v[144:145]
	v_pk_mul_f32 v[12:13], v[16:17], v[146:147]
	v_pk_mul_f32 v[14:15], v[24:25], v[144:145]
	v_pk_mul_f32 v[16:17], v[22:23], v[146:147]
	global_store_dwordx4 v[82:83], v[10:13], off offset:2048
	global_store_dwordx4 v[84:85], v[14:17], off offset:2048
	s_nop 0
	s_nop 0
	v_pk_mul_f32 v[2:3], v[2:3], v[148:149]
	v_pk_mul_f32 v[4:5], v[4:5], v[150:151]
	v_pk_mul_f32 v[6:7], v[6:7], v[148:149]
	v_pk_mul_f32 v[8:9], v[8:9], v[150:151]
	global_store_dwordx4 v[82:83], v[2:5], off offset:3072
	global_store_dwordx4 v[84:85], v[6:9], off offset:3072
	s_andn2_b64 exec, exec, s[2:3]
	s_cbranch_execnz .LBB0_1307
